# hand-written EpiResid fast path (bf16 in/out): 4-deep load ring, in-place pk math, batched lane reduce + atomics
# baseline (speedup 1.0000x reference)
.LBB0_215:
	s_cbranch_execz .LBB0_184
	s_and_b64 vcc, exec, s[72:73]
	s_cbranch_vccnz .Lce_fast
	s_waitcnt lgkmcnt(0)
	v_lshlrev_b64 v[128:129], 1, v[196:197]
	v_lshlrev_b64 v[130:131], 10, v[194:195]
	v_ashrrev_i32_e32 v199, 31, v198
	v_lshl_add_u64 v[142:143], v[200:201], 0, v[128:129]
	v_lshl_add_u64 v[150:151], v[130:131], 0, v[196:197]
	v_lshlrev_b64 v[130:131], 11, v[198:199]
	global_load_dwordx4 v[146:149], v[142:143], off
	global_load_dwordx4 v[136:139], v[142:143], off offset:256
	v_lshl_add_u64 v[130:131], s[54:55], 0, v[130:131]
	v_lshl_add_u64 v[140:141], v[130:131], 0, v[128:129]
	global_load_dwordx4 v[132:135], v[140:141], off
	global_load_dwordx4 v[128:131], v[140:141], off offset:256
	s_mov_b64 s[42:43], -1
	s_and_b64 vcc, exec, s[74:75]
	s_waitcnt vmcnt(0)
	v_lshlrev_b32_e32 v152, 16, v146
	v_and_b32_e32 v153, 0xffff0000, v146
	v_lshlrev_b32_e32 v146, 16, v147
	v_and_b32_e32 v147, 0xffff0000, v147
	v_pk_add_f32 v[126:127], v[126:127], v[146:147]
	v_lshlrev_b32_e32 v146, 16, v148
	v_and_b32_e32 v147, 0xffff0000, v148
	v_lshlrev_b32_e32 v148, 16, v149
	v_and_b32_e32 v149, 0xffff0000, v149
	v_pk_add_f32 v[124:125], v[124:125], v[152:153]
	v_pk_add_f32 v[122:123], v[122:123], v[148:149]
	v_pk_add_f32 v[120:121], v[120:121], v[146:147]
	v_lshl_add_u64 v[146:147], v[150:151], 2, s[94:95]
	s_cbranch_vccz .LBB0_218
	s_mov_b64 s[42:43], 0
	global_store_dwordx4 v[146:147], v[124:127], off
	global_store_dwordx4 v[146:147], v[120:123], off offset:16

.Lce_fast:
	v_lshlrev_b32_e32 v199, 11, v194
	v_lshl_add_u32 v199, v196, 1, v199
	global_load_dwordx4 v[128:131], v199, s[54:55]
	global_load_dwordx4 v[132:135], v199, s[54:55] offset:256
	v_add_u32_e32 v176, 0x8000, v199
	global_load_dwordx4 v[136:139], v176, s[54:55]
	global_load_dwordx4 v[140:143], v176, s[54:55] offset:256
	v_add_u32_e32 v177, 0x10000, v199
	global_load_dwordx4 v[154:157], v177, s[54:55]
	global_load_dwordx4 v[158:161], v177, s[54:55] offset:256
	v_add_u32_e32 v202, 0x18000, v199
	global_load_dwordx4 v[162:165], v202, s[54:55]
	global_load_dwordx4 v[166:169], v202, s[54:55] offset:256
	v_add_u32_e32 v203, 0x40000, v199
	v_add_u32_e32 v204, 0x48000, v199
	v_add_u32_e32 v205, 0x50000, v199
	v_add_u32_e32 v218, 0x58000, v199
	s_waitcnt vmcnt(6)
	v_lshlrev_b32_e32 v146, 16, v128
	v_and_b32_e32 v147, 0xffff0000, v128
	v_lshlrev_b32_e32 v148, 16, v129
	v_and_b32_e32 v149, 0xffff0000, v129
	v_lshlrev_b32_e32 v150, 16, v130
	v_and_b32_e32 v151, 0xffff0000, v130
	v_lshlrev_b32_e32 v152, 16, v131
	v_and_b32_e32 v153, 0xffff0000, v131
	v_pk_add_f32 v[124:125], v[124:125], v[146:147]
	v_pk_add_f32 v[126:127], v[126:127], v[148:149]
	v_pk_add_f32 v[120:121], v[120:121], v[150:151]
	v_pk_add_f32 v[122:123], v[122:123], v[152:153]
	v_cvt_pk_bf16_f32 v128, v124, v125
	v_cvt_pk_bf16_f32 v129, v126, v127
	v_cvt_pk_bf16_f32 v130, v120, v121
	v_cvt_pk_bf16_f32 v131, v122, v123
	global_store_dwordx4 v199, v[128:131], s[54:55]
	v_lshlrev_b32_e32 v146, 16, v132
	v_and_b32_e32 v147, 0xffff0000, v132
	v_lshlrev_b32_e32 v148, 16, v133
	v_and_b32_e32 v149, 0xffff0000, v133
	v_lshlrev_b32_e32 v150, 16, v134
	v_and_b32_e32 v151, 0xffff0000, v134
	v_lshlrev_b32_e32 v152, 16, v135
	v_and_b32_e32 v153, 0xffff0000, v135
	v_pk_add_f32 v[116:117], v[116:117], v[146:147]
	v_pk_add_f32 v[118:119], v[118:119], v[148:149]
	v_pk_add_f32 v[112:113], v[112:113], v[150:151]
	v_pk_add_f32 v[114:115], v[114:115], v[152:153]
	v_cvt_pk_bf16_f32 v132, v116, v117
	v_cvt_pk_bf16_f32 v133, v118, v119
	v_cvt_pk_bf16_f32 v134, v112, v113
	v_cvt_pk_bf16_f32 v135, v114, v115
	global_store_dwordx4 v199, v[132:135], s[54:55] offset:256
	global_load_dwordx4 v[128:131], v203, s[54:55]
	global_load_dwordx4 v[132:135], v203, s[54:55] offset:256
	v_pk_mul_f32 v[124:125], v[124:125], v[124:125]
	v_pk_mul_f32 v[116:117], v[116:117], v[116:117]
	v_pk_fma_f32 v[124:125], v[126:127], v[126:127], v[124:125]
	v_pk_fma_f32 v[116:117], v[118:119], v[118:119], v[116:117]
	v_pk_fma_f32 v[124:125], v[120:121], v[120:121], v[124:125]
	v_pk_fma_f32 v[116:117], v[112:113], v[112:113], v[116:117]
	v_pk_fma_f32 v[124:125], v[122:123], v[122:123], v[124:125]
	v_pk_fma_f32 v[116:117], v[114:115], v[114:115], v[116:117]
	v_pk_add_f32 v[124:125], v[124:125], v[116:117]
	v_add_f32_e32 v124, v124, v125
	s_waitcnt vmcnt(8)
	v_lshlrev_b32_e32 v146, 16, v136
	v_and_b32_e32 v147, 0xffff0000, v136
	v_lshlrev_b32_e32 v148, 16, v137
	v_and_b32_e32 v149, 0xffff0000, v137
	v_lshlrev_b32_e32 v150, 16, v138
	v_and_b32_e32 v151, 0xffff0000, v138
	v_lshlrev_b32_e32 v152, 16, v139
	v_and_b32_e32 v153, 0xffff0000, v139
	v_pk_add_f32 v[108:109], v[108:109], v[146:147]
	v_pk_add_f32 v[110:111], v[110:111], v[148:149]
	v_pk_add_f32 v[104:105], v[104:105], v[150:151]
	v_pk_add_f32 v[106:107], v[106:107], v[152:153]
	v_cvt_pk_bf16_f32 v136, v108, v109
	v_cvt_pk_bf16_f32 v137, v110, v111
	v_cvt_pk_bf16_f32 v138, v104, v105
	v_cvt_pk_bf16_f32 v139, v106, v107
	global_store_dwordx4 v176, v[136:139], s[54:55]
	v_lshlrev_b32_e32 v146, 16, v140
	v_and_b32_e32 v147, 0xffff0000, v140
	v_lshlrev_b32_e32 v148, 16, v141
	v_and_b32_e32 v149, 0xffff0000, v141
	v_lshlrev_b32_e32 v150, 16, v142
	v_and_b32_e32 v151, 0xffff0000, v142
	v_lshlrev_b32_e32 v152, 16, v143
	v_and_b32_e32 v153, 0xffff0000, v143
	v_pk_add_f32 v[100:101], v[100:101], v[146:147]
	v_pk_add_f32 v[102:103], v[102:103], v[148:149]
	v_pk_add_f32 v[96:97], v[96:97], v[150:151]
	v_pk_add_f32 v[98:99], v[98:99], v[152:153]
	v_cvt_pk_bf16_f32 v140, v100, v101
	v_cvt_pk_bf16_f32 v141, v102, v103
	v_cvt_pk_bf16_f32 v142, v96, v97
	v_cvt_pk_bf16_f32 v143, v98, v99
	global_store_dwordx4 v176, v[140:143], s[54:55] offset:256
	global_load_dwordx4 v[136:139], v204, s[54:55]
	global_load_dwordx4 v[140:143], v204, s[54:55] offset:256
	v_pk_mul_f32 v[108:109], v[108:109], v[108:109]
	v_pk_mul_f32 v[100:101], v[100:101], v[100:101]
	v_pk_fma_f32 v[108:109], v[110:111], v[110:111], v[108:109]
	v_pk_fma_f32 v[100:101], v[102:103], v[102:103], v[100:101]
	v_pk_fma_f32 v[108:109], v[104:105], v[104:105], v[108:109]
	v_pk_fma_f32 v[100:101], v[96:97], v[96:97], v[100:101]
	v_pk_fma_f32 v[108:109], v[106:107], v[106:107], v[108:109]
	v_pk_fma_f32 v[100:101], v[98:99], v[98:99], v[100:101]
	v_pk_add_f32 v[108:109], v[108:109], v[100:101]
	v_add_f32_e32 v108, v108, v109
	s_waitcnt vmcnt(10)
	v_lshlrev_b32_e32 v146, 16, v154
	v_and_b32_e32 v147, 0xffff0000, v154
	v_lshlrev_b32_e32 v148, 16, v155
	v_and_b32_e32 v149, 0xffff0000, v155
	v_lshlrev_b32_e32 v150, 16, v156
	v_and_b32_e32 v151, 0xffff0000, v156
	v_lshlrev_b32_e32 v152, 16, v157
	v_and_b32_e32 v153, 0xffff0000, v157
	v_pk_add_f32 v[92:93], v[92:93], v[146:147]
	v_pk_add_f32 v[94:95], v[94:95], v[148:149]
	v_pk_add_f32 v[88:89], v[88:89], v[150:151]
	v_pk_add_f32 v[90:91], v[90:91], v[152:153]
	v_cvt_pk_bf16_f32 v154, v92, v93
	v_cvt_pk_bf16_f32 v155, v94, v95
	v_cvt_pk_bf16_f32 v156, v88, v89
	v_cvt_pk_bf16_f32 v157, v90, v91
	global_store_dwordx4 v177, v[154:157], s[54:55]
	v_lshlrev_b32_e32 v146, 16, v158
	v_and_b32_e32 v147, 0xffff0000, v158
	v_lshlrev_b32_e32 v148, 16, v159
	v_and_b32_e32 v149, 0xffff0000, v159
	v_lshlrev_b32_e32 v150, 16, v160
	v_and_b32_e32 v151, 0xffff0000, v160
	v_lshlrev_b32_e32 v152, 16, v161
	v_and_b32_e32 v153, 0xffff0000, v161
	v_pk_add_f32 v[84:85], v[84:85], v[146:147]
	v_pk_add_f32 v[86:87], v[86:87], v[148:149]
	v_pk_add_f32 v[80:81], v[80:81], v[150:151]
	v_pk_add_f32 v[82:83], v[82:83], v[152:153]
	v_cvt_pk_bf16_f32 v158, v84, v85
	v_cvt_pk_bf16_f32 v159, v86, v87
	v_cvt_pk_bf16_f32 v160, v80, v81
	v_cvt_pk_bf16_f32 v161, v82, v83
	global_store_dwordx4 v177, v[158:161], s[54:55] offset:256
	global_load_dwordx4 v[154:157], v205, s[54:55]
	global_load_dwordx4 v[158:161], v205, s[54:55] offset:256
	v_pk_mul_f32 v[92:93], v[92:93], v[92:93]
	v_pk_mul_f32 v[84:85], v[84:85], v[84:85]
	v_pk_fma_f32 v[92:93], v[94:95], v[94:95], v[92:93]
	v_pk_fma_f32 v[84:85], v[86:87], v[86:87], v[84:85]
	v_pk_fma_f32 v[92:93], v[88:89], v[88:89], v[92:93]
	v_pk_fma_f32 v[84:85], v[80:81], v[80:81], v[84:85]
	v_pk_fma_f32 v[92:93], v[90:91], v[90:91], v[92:93]
	v_pk_fma_f32 v[84:85], v[82:83], v[82:83], v[84:85]
	v_pk_add_f32 v[92:93], v[92:93], v[84:85]
	v_add_f32_e32 v92, v92, v93
	s_waitcnt vmcnt(12)
	v_lshlrev_b32_e32 v146, 16, v162
	v_and_b32_e32 v147, 0xffff0000, v162
	v_lshlrev_b32_e32 v148, 16, v163
	v_and_b32_e32 v149, 0xffff0000, v163
	v_lshlrev_b32_e32 v150, 16, v164
	v_and_b32_e32 v151, 0xffff0000, v164
	v_lshlrev_b32_e32 v152, 16, v165
	v_and_b32_e32 v153, 0xffff0000, v165
	v_pk_add_f32 v[76:77], v[76:77], v[146:147]
	v_pk_add_f32 v[78:79], v[78:79], v[148:149]
	v_pk_add_f32 v[72:73], v[72:73], v[150:151]
	v_pk_add_f32 v[74:75], v[74:75], v[152:153]
	v_cvt_pk_bf16_f32 v162, v76, v77
	v_cvt_pk_bf16_f32 v163, v78, v79
	v_cvt_pk_bf16_f32 v164, v72, v73
	v_cvt_pk_bf16_f32 v165, v74, v75
	global_store_dwordx4 v202, v[162:165], s[54:55]
	v_lshlrev_b32_e32 v146, 16, v166
	v_and_b32_e32 v147, 0xffff0000, v166
	v_lshlrev_b32_e32 v148, 16, v167
	v_and_b32_e32 v149, 0xffff0000, v167
	v_lshlrev_b32_e32 v150, 16, v168
	v_and_b32_e32 v151, 0xffff0000, v168
	v_lshlrev_b32_e32 v152, 16, v169
	v_and_b32_e32 v153, 0xffff0000, v169
	v_pk_add_f32 v[68:69], v[68:69], v[146:147]
	v_pk_add_f32 v[70:71], v[70:71], v[148:149]
	v_pk_add_f32 v[64:65], v[64:65], v[150:151]
	v_pk_add_f32 v[66:67], v[66:67], v[152:153]
	v_cvt_pk_bf16_f32 v166, v68, v69
	v_cvt_pk_bf16_f32 v167, v70, v71
	v_cvt_pk_bf16_f32 v168, v64, v65
	v_cvt_pk_bf16_f32 v169, v66, v67
	global_store_dwordx4 v202, v[166:169], s[54:55] offset:256
	global_load_dwordx4 v[162:165], v218, s[54:55]
	global_load_dwordx4 v[166:169], v218, s[54:55] offset:256
	v_pk_mul_f32 v[76:77], v[76:77], v[76:77]
	v_pk_mul_f32 v[68:69], v[68:69], v[68:69]
	v_pk_fma_f32 v[76:77], v[78:79], v[78:79], v[76:77]
	v_pk_fma_f32 v[68:69], v[70:71], v[70:71], v[68:69]
	v_pk_fma_f32 v[76:77], v[72:73], v[72:73], v[76:77]
	v_pk_fma_f32 v[68:69], v[64:65], v[64:65], v[68:69]
	v_pk_fma_f32 v[76:77], v[74:75], v[74:75], v[76:77]
	v_pk_fma_f32 v[68:69], v[66:67], v[66:67], v[68:69]
	v_pk_add_f32 v[76:77], v[76:77], v[68:69]
	v_add_f32_e32 v76, v76, v77
	s_waitcnt vmcnt(12)
	v_lshlrev_b32_e32 v146, 16, v128
	v_and_b32_e32 v147, 0xffff0000, v128
	v_lshlrev_b32_e32 v148, 16, v129
	v_and_b32_e32 v149, 0xffff0000, v129
	v_lshlrev_b32_e32 v150, 16, v130
	v_and_b32_e32 v151, 0xffff0000, v130
	v_lshlrev_b32_e32 v152, 16, v131
	v_and_b32_e32 v153, 0xffff0000, v131
	v_pk_add_f32 v[60:61], v[60:61], v[146:147]
	v_pk_add_f32 v[62:63], v[62:63], v[148:149]
	v_pk_add_f32 v[56:57], v[56:57], v[150:151]
	v_pk_add_f32 v[58:59], v[58:59], v[152:153]
	v_cvt_pk_bf16_f32 v128, v60, v61
	v_cvt_pk_bf16_f32 v129, v62, v63
	v_cvt_pk_bf16_f32 v130, v56, v57
	v_cvt_pk_bf16_f32 v131, v58, v59
	global_store_dwordx4 v203, v[128:131], s[54:55]
	v_lshlrev_b32_e32 v146, 16, v132
	v_and_b32_e32 v147, 0xffff0000, v132
	v_lshlrev_b32_e32 v148, 16, v133
	v_and_b32_e32 v149, 0xffff0000, v133
	v_lshlrev_b32_e32 v150, 16, v134
	v_and_b32_e32 v151, 0xffff0000, v134
	v_lshlrev_b32_e32 v152, 16, v135
	v_and_b32_e32 v153, 0xffff0000, v135
	v_pk_add_f32 v[52:53], v[52:53], v[146:147]
	v_pk_add_f32 v[54:55], v[54:55], v[148:149]
	v_pk_add_f32 v[48:49], v[48:49], v[150:151]
	v_pk_add_f32 v[50:51], v[50:51], v[152:153]
	v_cvt_pk_bf16_f32 v132, v52, v53
	v_cvt_pk_bf16_f32 v133, v54, v55
	v_cvt_pk_bf16_f32 v134, v48, v49
	v_cvt_pk_bf16_f32 v135, v50, v51
	global_store_dwordx4 v203, v[132:135], s[54:55] offset:256
	v_pk_mul_f32 v[60:61], v[60:61], v[60:61]
	v_pk_mul_f32 v[52:53], v[52:53], v[52:53]
	v_pk_fma_f32 v[60:61], v[62:63], v[62:63], v[60:61]
	v_pk_fma_f32 v[52:53], v[54:55], v[54:55], v[52:53]
	v_pk_fma_f32 v[60:61], v[56:57], v[56:57], v[60:61]
	v_pk_fma_f32 v[52:53], v[48:49], v[48:49], v[52:53]
	v_pk_fma_f32 v[60:61], v[58:59], v[58:59], v[60:61]
	v_pk_fma_f32 v[52:53], v[50:51], v[50:51], v[52:53]
	v_pk_add_f32 v[60:61], v[60:61], v[52:53]
	v_add_f32_e32 v60, v60, v61
	s_waitcnt vmcnt(10)
	v_lshlrev_b32_e32 v146, 16, v136
	v_and_b32_e32 v147, 0xffff0000, v136
	v_lshlrev_b32_e32 v148, 16, v137
	v_and_b32_e32 v149, 0xffff0000, v137
	v_lshlrev_b32_e32 v150, 16, v138
	v_and_b32_e32 v151, 0xffff0000, v138
	v_lshlrev_b32_e32 v152, 16, v139
	v_and_b32_e32 v153, 0xffff0000, v139
	v_pk_add_f32 v[44:45], v[44:45], v[146:147]
	v_pk_add_f32 v[46:47], v[46:47], v[148:149]
	v_pk_add_f32 v[40:41], v[40:41], v[150:151]
	v_pk_add_f32 v[42:43], v[42:43], v[152:153]
	v_cvt_pk_bf16_f32 v136, v44, v45
	v_cvt_pk_bf16_f32 v137, v46, v47
	v_cvt_pk_bf16_f32 v138, v40, v41
	v_cvt_pk_bf16_f32 v139, v42, v43
	global_store_dwordx4 v204, v[136:139], s[54:55]
	v_lshlrev_b32_e32 v146, 16, v140
	v_and_b32_e32 v147, 0xffff0000, v140
	v_lshlrev_b32_e32 v148, 16, v141
	v_and_b32_e32 v149, 0xffff0000, v141
	v_lshlrev_b32_e32 v150, 16, v142
	v_and_b32_e32 v151, 0xffff0000, v142
	v_lshlrev_b32_e32 v152, 16, v143
	v_and_b32_e32 v153, 0xffff0000, v143
	v_pk_add_f32 v[36:37], v[36:37], v[146:147]
	v_pk_add_f32 v[38:39], v[38:39], v[148:149]
	v_pk_add_f32 v[32:33], v[32:33], v[150:151]
	v_pk_add_f32 v[34:35], v[34:35], v[152:153]
	v_cvt_pk_bf16_f32 v140, v36, v37
	v_cvt_pk_bf16_f32 v141, v38, v39
	v_cvt_pk_bf16_f32 v142, v32, v33
	v_cvt_pk_bf16_f32 v143, v34, v35
	global_store_dwordx4 v204, v[140:143], s[54:55] offset:256
	v_pk_mul_f32 v[44:45], v[44:45], v[44:45]
	v_pk_mul_f32 v[36:37], v[36:37], v[36:37]
	v_pk_fma_f32 v[44:45], v[46:47], v[46:47], v[44:45]
	v_pk_fma_f32 v[36:37], v[38:39], v[38:39], v[36:37]
	v_pk_fma_f32 v[44:45], v[40:41], v[40:41], v[44:45]
	v_pk_fma_f32 v[36:37], v[32:33], v[32:33], v[36:37]
	v_pk_fma_f32 v[44:45], v[42:43], v[42:43], v[44:45]
	v_pk_fma_f32 v[36:37], v[34:35], v[34:35], v[36:37]
	v_pk_add_f32 v[44:45], v[44:45], v[36:37]
	v_add_f32_e32 v44, v44, v45
	s_waitcnt vmcnt(8)
	v_lshlrev_b32_e32 v146, 16, v154
	v_and_b32_e32 v147, 0xffff0000, v154
	v_lshlrev_b32_e32 v148, 16, v155
	v_and_b32_e32 v149, 0xffff0000, v155
	v_lshlrev_b32_e32 v150, 16, v156
	v_and_b32_e32 v151, 0xffff0000, v156
	v_lshlrev_b32_e32 v152, 16, v157
	v_and_b32_e32 v153, 0xffff0000, v157
	v_pk_add_f32 v[28:29], v[28:29], v[146:147]
	v_pk_add_f32 v[30:31], v[30:31], v[148:149]
	v_pk_add_f32 v[24:25], v[24:25], v[150:151]
	v_pk_add_f32 v[26:27], v[26:27], v[152:153]
	v_cvt_pk_bf16_f32 v154, v28, v29
	v_cvt_pk_bf16_f32 v155, v30, v31
	v_cvt_pk_bf16_f32 v156, v24, v25
	v_cvt_pk_bf16_f32 v157, v26, v27
	global_store_dwordx4 v205, v[154:157], s[54:55]
	v_lshlrev_b32_e32 v146, 16, v158
	v_and_b32_e32 v147, 0xffff0000, v158
	v_lshlrev_b32_e32 v148, 16, v159
	v_and_b32_e32 v149, 0xffff0000, v159
	v_lshlrev_b32_e32 v150, 16, v160
	v_and_b32_e32 v151, 0xffff0000, v160
	v_lshlrev_b32_e32 v152, 16, v161
	v_and_b32_e32 v153, 0xffff0000, v161
	v_pk_add_f32 v[20:21], v[20:21], v[146:147]
	v_pk_add_f32 v[22:23], v[22:23], v[148:149]
	v_pk_add_f32 v[16:17], v[16:17], v[150:151]
	v_pk_add_f32 v[18:19], v[18:19], v[152:153]
	v_cvt_pk_bf16_f32 v158, v20, v21
	v_cvt_pk_bf16_f32 v159, v22, v23
	v_cvt_pk_bf16_f32 v160, v16, v17
	v_cvt_pk_bf16_f32 v161, v18, v19
	global_store_dwordx4 v205, v[158:161], s[54:55] offset:256
	v_pk_mul_f32 v[28:29], v[28:29], v[28:29]
	v_pk_mul_f32 v[20:21], v[20:21], v[20:21]
	v_pk_fma_f32 v[28:29], v[30:31], v[30:31], v[28:29]
	v_pk_fma_f32 v[20:21], v[22:23], v[22:23], v[20:21]
	v_pk_fma_f32 v[28:29], v[24:25], v[24:25], v[28:29]
	v_pk_fma_f32 v[20:21], v[16:17], v[16:17], v[20:21]
	v_pk_fma_f32 v[28:29], v[26:27], v[26:27], v[28:29]
	v_pk_fma_f32 v[20:21], v[18:19], v[18:19], v[20:21]
	v_pk_add_f32 v[28:29], v[28:29], v[20:21]
	v_add_f32_e32 v28, v28, v29
	s_waitcnt vmcnt(6)
	v_lshlrev_b32_e32 v146, 16, v162
	v_and_b32_e32 v147, 0xffff0000, v162
	v_lshlrev_b32_e32 v148, 16, v163
	v_and_b32_e32 v149, 0xffff0000, v163
	v_lshlrev_b32_e32 v150, 16, v164
	v_and_b32_e32 v151, 0xffff0000, v164
	v_lshlrev_b32_e32 v152, 16, v165
	v_and_b32_e32 v153, 0xffff0000, v165
	v_pk_add_f32 v[12:13], v[12:13], v[146:147]
	v_pk_add_f32 v[14:15], v[14:15], v[148:149]
	v_pk_add_f32 v[8:9], v[8:9], v[150:151]
	v_pk_add_f32 v[10:11], v[10:11], v[152:153]
	v_cvt_pk_bf16_f32 v162, v12, v13
	v_cvt_pk_bf16_f32 v163, v14, v15
	v_cvt_pk_bf16_f32 v164, v8, v9
	v_cvt_pk_bf16_f32 v165, v10, v11
	global_store_dwordx4 v218, v[162:165], s[54:55]
	v_lshlrev_b32_e32 v146, 16, v166
	v_and_b32_e32 v147, 0xffff0000, v166
	v_lshlrev_b32_e32 v148, 16, v167
	v_and_b32_e32 v149, 0xffff0000, v167
	v_lshlrev_b32_e32 v150, 16, v168
	v_and_b32_e32 v151, 0xffff0000, v168
	v_lshlrev_b32_e32 v152, 16, v169
	v_and_b32_e32 v153, 0xffff0000, v169
	v_pk_add_f32 v[4:5], v[4:5], v[146:147]
	v_pk_add_f32 v[6:7], v[6:7], v[148:149]
	v_pk_add_f32 v[0:1], v[0:1], v[150:151]
	v_pk_add_f32 v[2:3], v[2:3], v[152:153]
	v_cvt_pk_bf16_f32 v166, v4, v5
	v_cvt_pk_bf16_f32 v167, v6, v7
	v_cvt_pk_bf16_f32 v168, v0, v1
	v_cvt_pk_bf16_f32 v169, v2, v3
	global_store_dwordx4 v218, v[166:169], s[54:55] offset:256
	v_pk_mul_f32 v[12:13], v[12:13], v[12:13]
	v_pk_mul_f32 v[4:5], v[4:5], v[4:5]
	v_pk_fma_f32 v[12:13], v[14:15], v[14:15], v[12:13]
	v_pk_fma_f32 v[4:5], v[6:7], v[6:7], v[4:5]
	v_pk_fma_f32 v[12:13], v[8:9], v[8:9], v[12:13]
	v_pk_fma_f32 v[4:5], v[0:1], v[0:1], v[4:5]
	v_pk_fma_f32 v[12:13], v[10:11], v[10:11], v[12:13]
	v_pk_fma_f32 v[4:5], v[2:3], v[2:3], v[4:5]
	v_pk_add_f32 v[12:13], v[12:13], v[4:5]
	v_add_f32_e32 v12, v12, v13
	v_xor_b32_e32 v112, 16, v214
	v_xor_b32_e32 v113, 32, v214
	v_lshlrev_b32_e32 v112, 2, v112
	v_lshlrev_b32_e32 v113, 2, v113
	v_lshlrev_b32_e32 v114, 3, v194
	s_waitcnt lgkmcnt(0)
	ds_bpermute_b32 v120, v112, v124
	ds_bpermute_b32 v104, v112, v108
	ds_bpermute_b32 v88, v112, v92
	ds_bpermute_b32 v72, v112, v76
	ds_bpermute_b32 v56, v112, v60
	ds_bpermute_b32 v40, v112, v44
	ds_bpermute_b32 v24, v112, v28
	ds_bpermute_b32 v8, v112, v12
	s_waitcnt lgkmcnt(7)
	v_add_f32_e32 v124, v124, v120
	ds_bpermute_b32 v120, v113, v124
	s_waitcnt lgkmcnt(7)
	v_add_f32_e32 v108, v108, v104
	ds_bpermute_b32 v104, v113, v108
	s_waitcnt lgkmcnt(7)
	v_add_f32_e32 v92, v92, v88
	ds_bpermute_b32 v88, v113, v92
	s_waitcnt lgkmcnt(7)
	v_add_f32_e32 v76, v76, v72
	ds_bpermute_b32 v72, v113, v76
	s_waitcnt lgkmcnt(7)
	v_add_f32_e32 v60, v60, v56
	ds_bpermute_b32 v56, v113, v60
	s_waitcnt lgkmcnt(7)
	v_add_f32_e32 v44, v44, v40
	ds_bpermute_b32 v40, v113, v44
	s_waitcnt lgkmcnt(7)
	v_add_f32_e32 v28, v28, v24
	ds_bpermute_b32 v24, v113, v28
	s_waitcnt lgkmcnt(7)
	v_add_f32_e32 v12, v12, v8
	ds_bpermute_b32 v8, v113, v12
	s_and_saveexec_b64 s[42:43], s[38:39]
	s_waitcnt lgkmcnt(7)
	v_add_f32_e32 v124, v124, v120
	v_fma_f32 v124, v124, s91, 0.5
	v_trunc_f32_e32 v124, v124
	v_mul_f32_e32 v125, 0x2f800000, v124
	v_floor_f32_e32 v125, v125
	v_fmac_f32_e32 v124, 0xcf800000, v125
	v_cvt_u32_f32_e32 v124, v124
	v_cvt_u32_f32_e32 v125, v125
	global_atomic_add_x2 v114, v[124:125], s[52:53]
	s_waitcnt lgkmcnt(6)
	v_add_f32_e32 v108, v108, v104
	v_fma_f32 v108, v108, s91, 0.5
	v_trunc_f32_e32 v108, v108
	v_mul_f32_e32 v109, 0x2f800000, v108
	v_floor_f32_e32 v109, v109
	v_fmac_f32_e32 v108, 0xcf800000, v109
	v_cvt_u32_f32_e32 v108, v108
	v_cvt_u32_f32_e32 v109, v109
	global_atomic_add_x2 v114, v[108:109], s[52:53] offset:128
	s_waitcnt lgkmcnt(5)
	v_add_f32_e32 v92, v92, v88
	v_fma_f32 v92, v92, s91, 0.5
	v_trunc_f32_e32 v92, v92
	v_mul_f32_e32 v93, 0x2f800000, v92
	v_floor_f32_e32 v93, v93
	v_fmac_f32_e32 v92, 0xcf800000, v93
	v_cvt_u32_f32_e32 v92, v92
	v_cvt_u32_f32_e32 v93, v93
	global_atomic_add_x2 v114, v[92:93], s[52:53] offset:256
	s_waitcnt lgkmcnt(4)
	v_add_f32_e32 v76, v76, v72
	v_fma_f32 v76, v76, s91, 0.5
	v_trunc_f32_e32 v76, v76
	v_mul_f32_e32 v77, 0x2f800000, v76
	v_floor_f32_e32 v77, v77
	v_fmac_f32_e32 v76, 0xcf800000, v77
	v_cvt_u32_f32_e32 v76, v76
	v_cvt_u32_f32_e32 v77, v77
	global_atomic_add_x2 v114, v[76:77], s[52:53] offset:384
	s_waitcnt lgkmcnt(3)
	v_add_f32_e32 v60, v60, v56
	v_fma_f32 v60, v60, s91, 0.5
	v_trunc_f32_e32 v60, v60
	v_mul_f32_e32 v61, 0x2f800000, v60
	v_floor_f32_e32 v61, v61
	v_fmac_f32_e32 v60, 0xcf800000, v61
	v_cvt_u32_f32_e32 v60, v60
	v_cvt_u32_f32_e32 v61, v61
	global_atomic_add_x2 v114, v[60:61], s[52:53] offset:1024
	s_waitcnt lgkmcnt(2)
	v_add_f32_e32 v44, v44, v40
	v_fma_f32 v44, v44, s91, 0.5
	v_trunc_f32_e32 v44, v44
	v_mul_f32_e32 v45, 0x2f800000, v44
	v_floor_f32_e32 v45, v45
	v_fmac_f32_e32 v44, 0xcf800000, v45
	v_cvt_u32_f32_e32 v44, v44
	v_cvt_u32_f32_e32 v45, v45
	global_atomic_add_x2 v114, v[44:45], s[52:53] offset:1152
	s_waitcnt lgkmcnt(1)
	v_add_f32_e32 v28, v28, v24
	v_fma_f32 v28, v28, s91, 0.5
	v_trunc_f32_e32 v28, v28
	v_mul_f32_e32 v29, 0x2f800000, v28
	v_floor_f32_e32 v29, v29
	v_fmac_f32_e32 v28, 0xcf800000, v29
	v_cvt_u32_f32_e32 v28, v28
	v_cvt_u32_f32_e32 v29, v29
	global_atomic_add_x2 v114, v[28:29], s[52:53] offset:1280
	s_waitcnt lgkmcnt(0)
	v_add_f32_e32 v12, v12, v8
	v_fma_f32 v12, v12, s91, 0.5
	v_trunc_f32_e32 v12, v12
	v_mul_f32_e32 v13, 0x2f800000, v12
	v_floor_f32_e32 v13, v13
	v_fmac_f32_e32 v12, 0xcf800000, v13
	v_cvt_u32_f32_e32 v12, v12
	v_cvt_u32_f32_e32 v13, v13
	global_atomic_add_x2 v114, v[12:13], s[52:53] offset:1408
	s_branch .LBB0_182
